# P2 gdn_prep substitution blocks: the 16 serialized LDS round trips forming the row scale factors merged (reads up front, one wait, then the 16 mul/exp/mul)
# speedup vs baseline: 1.0152x; 1.0152x over previous
; DEV float bf2f(unsigned b) { return __uint_as_float(b << 16); }
; DEV void gdn_prep_chunk(const Params& p, int item, unsigned char* lds) {
;     ...
;         for (int ib = 0; ib < 4; ++ib) {
;             f32x2_t acc[8];
; #pragma unroll
;             for (int r = 0; r < 16; ++r) { const int j = ib * 16 + r; float f = bts[j]; if (isw) f *= __expf(gcs[j]); acc[r >> 1][r & 1] = f * bf2f(src[j * QS + cc]); }
.LBB0_577:
	s_lshl_b32 s34, s37, 6
	s_add_i32 s69, s39, s34
	v_mov_b32_e32 v2, s69
	ds_read_b32 v3, v2 offset:52480
	ds_read_b32 v200, v2 offset:52224
	ds_read_b32 v201, v2 offset:52228
	ds_read_b32 v202, v2 offset:52232
	ds_read_b32 v203, v2 offset:52236
	ds_read_b32 v204, v2 offset:52240
	ds_read_b32 v205, v2 offset:52244
	ds_read_b32 v206, v2 offset:52248
	ds_read_b32 v207, v2 offset:52252
	ds_read_b32 v208, v2 offset:52256
	ds_read_b32 v209, v2 offset:52260
	ds_read_b32 v210, v2 offset:52264
	ds_read_b32 v211, v2 offset:52268
	ds_read_b32 v212, v2 offset:52272
	ds_read_b32 v213, v2 offset:52276
	ds_read_b32 v214, v2 offset:52280
	ds_read_b32 v215, v2 offset:52284


; DEV float bf2f(unsigned b) { return __uint_as_float(b << 16); }
; DEV void gdn_prep_chunk(const Params& p, int item, unsigned char* lds) {
;     ...
;         for (int ib = 0; ib < 4; ++ib) {
;             f32x2_t acc[8];
; #pragma unroll
;             for (int r = 0; r < 16; ++r) { const int j = ib * 16 + r; float f = bts[j]; if (isw) f *= __expf(gcs[j]); acc[r >> 1][r & 1] = f * bf2f(src[j * QS + cc]); }
.LBB0_579:

; DEV float bf2f(unsigned b) { return __uint_as_float(b << 16); }
; DEV void gdn_prep_chunk(const Params& p, int item, unsigned char* lds) {
;     ...
;         for (int ib = 0; ib < 4; ++ib) {
;             f32x2_t acc[8];
; #pragma unroll
;             for (int r = 0; r < 16; ++r) { const int j = ib * 16 + r; float f = bts[j]; if (isw) f *= __expf(gcs[j]); acc[r >> 1][r & 1] = f * bf2f(src[j * QS + cc]); }
	s_mul_i32 s70, s37, 0x1100
	v_add_u32_e32 v142, s70, v188
	v_mov_b32_e32 v2, s69
	ds_read_u16 v5, v142
	ds_read_b32 v4, v2 offset:52484


; DEV float bf2f(unsigned b) { return __uint_as_float(b << 16); }
; DEV void gdn_prep_chunk(const Params& p, int item, unsigned char* lds) {
;     ...
;         for (int ib = 0; ib < 4; ++ib) {
;             f32x2_t acc[8];
; #pragma unroll
;             for (int r = 0; r < 16; ++r) { const int j = ib * 16 + r; float f = bts[j]; if (isw) f *= __expf(gcs[j]); acc[r >> 1][r & 1] = f * bf2f(src[j * QS + cc]); }
.LBB0_581:

; DEV float bf2f(unsigned b) { return __uint_as_float(b << 16); }
; DEV void gdn_prep_chunk(const Params& p, int item, unsigned char* lds) {
;     ...
;         for (int ib = 0; ib < 4; ++ib) {
;             f32x2_t acc[8];
; #pragma unroll
;             for (int r = 0; r < 16; ++r) { const int j = ib * 16 + r; float f = bts[j]; if (isw) f *= __expf(gcs[j]); acc[r >> 1][r & 1] = f * bf2f(src[j * QS + cc]); }
	s_lshl_b32 s67, s37, 4
	s_or_b32 s68, s67, 1
	s_mul_i32 s71, s68, 0x110
	v_add_u32_e32 v194, s71, v188
	v_mov_b32_e32 v2, s69
	ds_read_u16 v6, v194
	ds_read_b32 v2, v2 offset:52488


; DEV float bf2f(unsigned b) { return __uint_as_float(b << 16); }
; DEV void gdn_prep_chunk(const Params& p, int item, unsigned char* lds) {
;     ...
;         for (int ib = 0; ib < 4; ++ib) {
;             f32x2_t acc[8];
; #pragma unroll
;             for (int r = 0; r < 16; ++r) { const int j = ib * 16 + r; float f = bts[j]; if (isw) f *= __expf(gcs[j]); acc[r >> 1][r & 1] = f * bf2f(src[j * QS + cc]); }
.LBB0_583:

; DEV float bf2f(unsigned b) { return __uint_as_float(b << 16); }
; DEV void gdn_prep_chunk(const Params& p, int item, unsigned char* lds) {
;     ...
;         for (int ib = 0; ib < 4; ++ib) {
;             f32x2_t acc[8];
; #pragma unroll
;             for (int r = 0; r < 16; ++r) { const int j = ib * 16 + r; float f = bts[j]; if (isw) f *= __expf(gcs[j]); acc[r >> 1][r & 1] = f * bf2f(src[j * QS + cc]); }
	s_add_i32 s72, s71, 0x110
	v_add_u32_e32 v193, s72, v188
	v_mov_b32_e32 v7, s69
	ds_read_u16 v8, v193
	ds_read_b32 v7, v7 offset:52492


; DEV float bf2f(unsigned b) { return __uint_as_float(b << 16); }
; DEV void gdn_prep_chunk(const Params& p, int item, unsigned char* lds) {
;     ...
;         for (int ib = 0; ib < 4; ++ib) {
;             f32x2_t acc[8];
; #pragma unroll
;             for (int r = 0; r < 16; ++r) { const int j = ib * 16 + r; float f = bts[j]; if (isw) f *= __expf(gcs[j]); acc[r >> 1][r & 1] = f * bf2f(src[j * QS + cc]); }
.LBB0_585:

; DEV float bf2f(unsigned b) { return __uint_as_float(b << 16); }
; DEV void gdn_prep_chunk(const Params& p, int item, unsigned char* lds) {
;     ...
;         for (int ib = 0; ib < 4; ++ib) {
;             f32x2_t acc[8];
; #pragma unroll
;             for (int r = 0; r < 16; ++r) { const int j = ib * 16 + r; float f = bts[j]; if (isw) f *= __expf(gcs[j]); acc[r >> 1][r & 1] = f * bf2f(src[j * QS + cc]); }
	s_addk_i32 s72, 0x110
	v_add_u32_e32 v192, s72, v188
	v_mov_b32_e32 v10, s69
	ds_read_u16 v9, v192
	ds_read_b32 v10, v10 offset:52496


; DEV float bf2f(unsigned b) { return __uint_as_float(b << 16); }
; DEV void gdn_prep_chunk(const Params& p, int item, unsigned char* lds) {
;     ...
;         for (int ib = 0; ib < 4; ++ib) {
;             f32x2_t acc[8];
; #pragma unroll
;             for (int r = 0; r < 16; ++r) { const int j = ib * 16 + r; float f = bts[j]; if (isw) f *= __expf(gcs[j]); acc[r >> 1][r & 1] = f * bf2f(src[j * QS + cc]); }
.LBB0_587:

; DEV float bf2f(unsigned b) { return __uint_as_float(b << 16); }
; DEV void gdn_prep_chunk(const Params& p, int item, unsigned char* lds) {
;     ...
;         for (int ib = 0; ib < 4; ++ib) {
;             f32x2_t acc[8];
; #pragma unroll
;             for (int r = 0; r < 16; ++r) { const int j = ib * 16 + r; float f = bts[j]; if (isw) f *= __expf(gcs[j]); acc[r >> 1][r & 1] = f * bf2f(src[j * QS + cc]); }
	s_addk_i32 s72, 0x110
	v_add_u32_e32 v191, s72, v188
	v_mov_b32_e32 v11, s69
	ds_read_u16 v12, v191
	ds_read_b32 v11, v11 offset:52500


; DEV float bf2f(unsigned b) { return __uint_as_float(b << 16); }
; DEV void gdn_prep_chunk(const Params& p, int item, unsigned char* lds) {
;     ...
;         for (int ib = 0; ib < 4; ++ib) {
;             f32x2_t acc[8];
; #pragma unroll
;             for (int r = 0; r < 16; ++r) { const int j = ib * 16 + r; float f = bts[j]; if (isw) f *= __expf(gcs[j]); acc[r >> 1][r & 1] = f * bf2f(src[j * QS + cc]); }
.LBB0_589:

; DEV float bf2f(unsigned b) { return __uint_as_float(b << 16); }
; DEV void gdn_prep_chunk(const Params& p, int item, unsigned char* lds) {
;     ...
;         for (int ib = 0; ib < 4; ++ib) {
;             f32x2_t acc[8];
; #pragma unroll
;             for (int r = 0; r < 16; ++r) { const int j = ib * 16 + r; float f = bts[j]; if (isw) f *= __expf(gcs[j]); acc[r >> 1][r & 1] = f * bf2f(src[j * QS + cc]); }
	s_addk_i32 s72, 0x110
	v_add_u32_e32 v190, s72, v188
	v_mov_b32_e32 v14, s69
	ds_read_u16 v13, v190
	ds_read_b32 v14, v14 offset:52504


; DEV float bf2f(unsigned b) { return __uint_as_float(b << 16); }
; DEV void gdn_prep_chunk(const Params& p, int item, unsigned char* lds) {
;     ...
;         for (int ib = 0; ib < 4; ++ib) {
;             f32x2_t acc[8];
; #pragma unroll
;             for (int r = 0; r < 16; ++r) { const int j = ib * 16 + r; float f = bts[j]; if (isw) f *= __expf(gcs[j]); acc[r >> 1][r & 1] = f * bf2f(src[j * QS + cc]); }
.LBB0_591:

; DEV float bf2f(unsigned b) { return __uint_as_float(b << 16); }
; DEV void gdn_prep_chunk(const Params& p, int item, unsigned char* lds) {
;     ...
;         for (int ib = 0; ib < 4; ++ib) {
;             f32x2_t acc[8];
; #pragma unroll
;             for (int r = 0; r < 16; ++r) { const int j = ib * 16 + r; float f = bts[j]; if (isw) f *= __expf(gcs[j]); acc[r >> 1][r & 1] = f * bf2f(src[j * QS + cc]); }
	s_addk_i32 s72, 0x110
	v_add_u32_e32 v189, s72, v188
	v_mov_b32_e32 v15, s69
	ds_read_u16 v16, v189
	ds_read_b32 v15, v15 offset:52508


; DEV float bf2f(unsigned b) { return __uint_as_float(b << 16); }
; DEV void gdn_prep_chunk(const Params& p, int item, unsigned char* lds) {
;     ...
;         for (int ib = 0; ib < 4; ++ib) {
;             f32x2_t acc[8];
; #pragma unroll
;             for (int r = 0; r < 16; ++r) { const int j = ib * 16 + r; float f = bts[j]; if (isw) f *= __expf(gcs[j]); acc[r >> 1][r & 1] = f * bf2f(src[j * QS + cc]); }
.LBB0_593:

; DEV float bf2f(unsigned b) { return __uint_as_float(b << 16); }
; DEV void gdn_prep_chunk(const Params& p, int item, unsigned char* lds) {
;     ...
;         for (int ib = 0; ib < 4; ++ib) {
;             f32x2_t acc[8];
; #pragma unroll
;             for (int r = 0; r < 16; ++r) { const int j = ib * 16 + r; float f = bts[j]; if (isw) f *= __expf(gcs[j]); acc[r >> 1][r & 1] = f * bf2f(src[j * QS + cc]); }
	v_mov_b32_e32 v18, s69
	ds_read_u16 v17, v189 offset:272
	ds_read_b32 v18, v18 offset:52512


; DEV float bf2f(unsigned b) { return __uint_as_float(b << 16); }
; DEV void gdn_prep_chunk(const Params& p, int item, unsigned char* lds) {
;     ...
;         for (int ib = 0; ib < 4; ++ib) {
;             f32x2_t acc[8];
; #pragma unroll
;             for (int r = 0; r < 16; ++r) { const int j = ib * 16 + r; float f = bts[j]; if (isw) f *= __expf(gcs[j]); acc[r >> 1][r & 1] = f * bf2f(src[j * QS + cc]); }
.LBB0_595:

; DEV float bf2f(unsigned b) { return __uint_as_float(b << 16); }
; DEV void gdn_prep_chunk(const Params& p, int item, unsigned char* lds) {
;     ...
;         for (int ib = 0; ib < 4; ++ib) {
;             f32x2_t acc[8];
; #pragma unroll
;             for (int r = 0; r < 16; ++r) { const int j = ib * 16 + r; float f = bts[j]; if (isw) f *= __expf(gcs[j]); acc[r >> 1][r & 1] = f * bf2f(src[j * QS + cc]); }
	v_mov_b32_e32 v19, s69
	ds_read_u16 v20, v189 offset:544
	ds_read_b32 v19, v19 offset:52516


; DEV float bf2f(unsigned b) { return __uint_as_float(b << 16); }
; DEV void gdn_prep_chunk(const Params& p, int item, unsigned char* lds) {
;     ...
;         for (int ib = 0; ib < 4; ++ib) {
;             f32x2_t acc[8];
; #pragma unroll
;             for (int r = 0; r < 16; ++r) { const int j = ib * 16 + r; float f = bts[j]; if (isw) f *= __expf(gcs[j]); acc[r >> 1][r & 1] = f * bf2f(src[j * QS + cc]); }
.LBB0_597:

; DEV float bf2f(unsigned b) { return __uint_as_float(b << 16); }
; DEV void gdn_prep_chunk(const Params& p, int item, unsigned char* lds) {
;     ...
;         for (int ib = 0; ib < 4; ++ib) {
;             f32x2_t acc[8];
; #pragma unroll
;             for (int r = 0; r < 16; ++r) { const int j = ib * 16 + r; float f = bts[j]; if (isw) f *= __expf(gcs[j]); acc[r >> 1][r & 1] = f * bf2f(src[j * QS + cc]); }
	v_mov_b32_e32 v22, s69
	ds_read_u16 v21, v189 offset:816
	ds_read_b32 v23, v22 offset:52520


; DEV float bf2f(unsigned b) { return __uint_as_float(b << 16); }
; DEV void gdn_prep_chunk(const Params& p, int item, unsigned char* lds) {
;     ...
;         for (int ib = 0; ib < 4; ++ib) {
;             f32x2_t acc[8];
; #pragma unroll
;             for (int r = 0; r < 16; ++r) { const int j = ib * 16 + r; float f = bts[j]; if (isw) f *= __expf(gcs[j]); acc[r >> 1][r & 1] = f * bf2f(src[j * QS + cc]); }
.LBB0_599:

; DEV float bf2f(unsigned b) { return __uint_as_float(b << 16); }
; DEV void gdn_prep_chunk(const Params& p, int item, unsigned char* lds) {
;     ...
;         for (int ib = 0; ib < 4; ++ib) {
;             f32x2_t acc[8];
; #pragma unroll
;             for (int r = 0; r < 16; ++r) { const int j = ib * 16 + r; float f = bts[j]; if (isw) f *= __expf(gcs[j]); acc[r >> 1][r & 1] = f * bf2f(src[j * QS + cc]); }
	v_mov_b32_e32 v22, s69
	ds_read_u16 v25, v189 offset:1088
	ds_read_b32 v22, v22 offset:52524


; DEV float bf2f(unsigned b) { return __uint_as_float(b << 16); }
; DEV void gdn_prep_chunk(const Params& p, int item, unsigned char* lds) {
;     ...
;         for (int ib = 0; ib < 4; ++ib) {
;             f32x2_t acc[8];
; #pragma unroll
;             for (int r = 0; r < 16; ++r) { const int j = ib * 16 + r; float f = bts[j]; if (isw) f *= __expf(gcs[j]); acc[r >> 1][r & 1] = f * bf2f(src[j * QS + cc]); }
.LBB0_601:

; DEV float bf2f(unsigned b) { return __uint_as_float(b << 16); }
; DEV void gdn_prep_chunk(const Params& p, int item, unsigned char* lds) {
;     ...
;         for (int ib = 0; ib < 4; ++ib) {
;             f32x2_t acc[8];
; #pragma unroll
;             for (int r = 0; r < 16; ++r) { const int j = ib * 16 + r; float f = bts[j]; if (isw) f *= __expf(gcs[j]); acc[r >> 1][r & 1] = f * bf2f(src[j * QS + cc]); }
	v_mov_b32_e32 v26, s69
	ds_read_u16 v24, v189 offset:1360
	ds_read_b32 v27, v26 offset:52528


; DEV float bf2f(unsigned b) { return __uint_as_float(b << 16); }
; DEV void gdn_prep_chunk(const Params& p, int item, unsigned char* lds) {
;     ...
;         for (int ib = 0; ib < 4; ++ib) {
;             f32x2_t acc[8];
; #pragma unroll
;             for (int r = 0; r < 16; ++r) { const int j = ib * 16 + r; float f = bts[j]; if (isw) f *= __expf(gcs[j]); acc[r >> 1][r & 1] = f * bf2f(src[j * QS + cc]); }
.LBB0_603:

; DEV float bf2f(unsigned b) { return __uint_as_float(b << 16); }
; DEV void gdn_prep_chunk(const Params& p, int item, unsigned char* lds) {
;     ...
;         for (int ib = 0; ib < 4; ++ib) {
;             f32x2_t acc[8];
; #pragma unroll
;             for (int r = 0; r < 16; ++r) { const int j = ib * 16 + r; float f = bts[j]; if (isw) f *= __expf(gcs[j]); acc[r >> 1][r & 1] = f * bf2f(src[j * QS + cc]); }
	v_mov_b32_e32 v26, s69
	ds_read_u16 v30, v189 offset:1632
	ds_read_b32 v26, v26 offset:52532


; DEV float bf2f(unsigned b) { return __uint_as_float(b << 16); }
; DEV void gdn_prep_chunk(const Params& p, int item, unsigned char* lds) {
;     ...
;         for (int ib = 0; ib < 4; ++ib) {
;             f32x2_t acc[8];
; #pragma unroll
;             for (int r = 0; r < 16; ++r) { const int j = ib * 16 + r; float f = bts[j]; if (isw) f *= __expf(gcs[j]); acc[r >> 1][r & 1] = f * bf2f(src[j * QS + cc]); }
.LBB0_605:

; DEV float bf2f(unsigned b) { return __uint_as_float(b << 16); }
; DEV void gdn_prep_chunk(const Params& p, int item, unsigned char* lds) {
;     ...
;         for (int ib = 0; ib < 4; ++ib) {
;             f32x2_t acc[8];
; #pragma unroll
;             for (int r = 0; r < 16; ++r) { const int j = ib * 16 + r; float f = bts[j]; if (isw) f *= __expf(gcs[j]); acc[r >> 1][r & 1] = f * bf2f(src[j * QS + cc]); }
	v_mov_b32_e32 v29, s69
	ds_read_u16 v28, v189 offset:1904
	ds_read_b32 v31, v29 offset:52536


; DEV float bf2f(unsigned b) { return __uint_as_float(b << 16); }
; DEV void gdn_prep_chunk(const Params& p, int item, unsigned char* lds) {
;     ...
;         for (int ib = 0; ib < 4; ++ib) {
;             f32x2_t acc[8];
; #pragma unroll
;             for (int r = 0; r < 16; ++r) { const int j = ib * 16 + r; float f = bts[j]; if (isw) f *= __expf(gcs[j]); acc[r >> 1][r & 1] = f * bf2f(src[j * QS + cc]); }
.LBB0_607:

; DEV float bf2f(unsigned b) { return __uint_as_float(b << 16); }
; DEV void gdn_prep_chunk(const Params& p, int item, unsigned char* lds) {
;     ...
;         for (int ib = 0; ib < 4; ++ib) {
;             f32x2_t acc[8];
; #pragma unroll
;             for (int r = 0; r < 16; ++r) { const int j = ib * 16 + r; float f = bts[j]; if (isw) f *= __expf(gcs[j]); acc[r >> 1][r & 1] = f * bf2f(src[j * QS + cc]); }
	v_mov_b32_e32 v29, s69
	ds_read_u16 v32, v189 offset:2176
	ds_read_b32 v29, v29 offset:52540


; DEV float bf2f(unsigned b) { return __uint_as_float(b << 16); }
; DEV void gdn_prep_chunk(const Params& p, int item, unsigned char* lds) {
;     ...
;         for (int ib = 0; ib < 4; ++ib) {
;             f32x2_t acc[8];
; #pragma unroll
;             for (int r = 0; r < 16; ++r) { const int j = ib * 16 + r; float f = bts[j]; if (isw) f *= __expf(gcs[j]); acc[r >> 1][r & 1] = f * bf2f(src[j * QS + cc]); }
.LBB0_609:
	s_waitcnt lgkmcnt(0)
	s_and_saveexec_b64 s[34:35], s[4:5]
	s_cbranch_execz .Lsubinit_skip
	v_mul_f32_e32 v200, 0x3fb8aa3b, v200
	v_mul_f32_e32 v201, 0x3fb8aa3b, v201
	v_mul_f32_e32 v202, 0x3fb8aa3b, v202
	v_mul_f32_e32 v203, 0x3fb8aa3b, v203
	v_mul_f32_e32 v204, 0x3fb8aa3b, v204
	v_mul_f32_e32 v205, 0x3fb8aa3b, v205
	v_mul_f32_e32 v206, 0x3fb8aa3b, v206
	v_mul_f32_e32 v207, 0x3fb8aa3b, v207
	v_mul_f32_e32 v208, 0x3fb8aa3b, v208
	v_mul_f32_e32 v209, 0x3fb8aa3b, v209
	v_mul_f32_e32 v210, 0x3fb8aa3b, v210
	v_mul_f32_e32 v211, 0x3fb8aa3b, v211
	v_mul_f32_e32 v212, 0x3fb8aa3b, v212
	v_mul_f32_e32 v213, 0x3fb8aa3b, v213
	v_mul_f32_e32 v214, 0x3fb8aa3b, v214
	v_mul_f32_e32 v215, 0x3fb8aa3b, v215
	v_exp_f32_e32 v200, v200
	v_exp_f32_e32 v201, v201
	v_exp_f32_e32 v202, v202
	v_exp_f32_e32 v203, v203
	v_exp_f32_e32 v204, v204
	v_exp_f32_e32 v205, v205
	v_exp_f32_e32 v206, v206
	v_exp_f32_e32 v207, v207
	v_exp_f32_e32 v208, v208
	v_exp_f32_e32 v209, v209
	v_exp_f32_e32 v210, v210
	v_exp_f32_e32 v211, v211
	v_exp_f32_e32 v212, v212
	v_exp_f32_e32 v213, v213
	v_exp_f32_e32 v214, v214
	v_exp_f32_e32 v215, v215
	s_nop 0
	v_mul_f32_e32 v3, v3, v200
	v_mul_f32_e32 v4, v4, v201
	v_mul_f32_e32 v2, v2, v202
	v_mul_f32_e32 v7, v7, v203
	v_mul_f32_e32 v10, v10, v204
	v_mul_f32_e32 v11, v11, v205
	v_mul_f32_e32 v14, v14, v206
	v_mul_f32_e32 v15, v15, v207
	v_mul_f32_e32 v18, v18, v208
	v_mul_f32_e32 v19, v19, v209
	v_mul_f32_e32 v23, v23, v210
	v_mul_f32_e32 v22, v22, v211
	v_mul_f32_e32 v27, v27, v212
	v_mul_f32_e32 v26, v26, v213
	v_mul_f32_e32 v31, v31, v214
	v_mul_f32_e32 v29, v29, v215
